# GQA loop: K-fragment LDS reads of the QK chain issued at the loop header before the DMA block, ks0 consumed last
# baseline (speedup 1.0000x reference)
.LBB0_135:
	s_and_b32 s46, s45, 0x4000
	v_add_u32_e32 v188, s46, v242
	v_add_u32_e32 v162, v188, v244
	v_add_u32_e32 v161, v188, v245
	v_add_u32_e32 v160, v188, v246
	v_add_u32_e32 v163, v188, v243
	ds_read_b128 v[164:167], v162
	ds_read_b128 v[168:171], v162 offset:4096
	ds_read_b128 v[172:175], v161
	ds_read_b128 v[176:179], v161 offset:4096
	ds_read_b128 v[180:183], v160
	ds_read_b128 v[184:187], v160 offset:4096
	s_add_i32 s2, s10, 2
	s_cmp_ge_u32 s2, s8
	s_cbranch_scc1 .LBB0_137
	s_add_i32 s2, s13, s10
	s_add_i32 s70, s2, 2
	s_lshl_b64 s[2:3], s[70:71], 13
	s_add_u32 s2, s17, s2
	s_addc_u32 s3, s18, s3
	s_cmp_lg_u32 32, -1
	s_cselect_b32 s42, 32, 0
	s_sub_i32 s42, s42, s46
	s_addk_i32 s42, 0x4000
	v_add_u32_e32 v66, s42, v213
	v_lshl_add_u64 v[64:65], v[192:193], 1, s[2:3]
	v_readfirstlane_b32 s43, v66
	s_mov_b32 m0, s43
	v_add_u32_e32 v67, s42, v241
	global_load_lds_dwordx4 v[64:65], off
	v_lshl_add_u64 v[64:65], v[216:217], 1, s[2:3]
	v_readfirstlane_b32 s2, v67
	s_mov_b32 m0, s2
	s_lshl_b64 s[2:3], s[70:71], 7
	s_add_u32 s2, s19, s2
	v_add_u32_e32 v66, 0x2000, v66
	s_addc_u32 s3, s44, s3
	v_readfirstlane_b32 s42, v66
	global_load_lds_dwordx4 v[64:65], off
	v_lshl_add_u64 v[64:65], v[214:215], 1, s[2:3]
	s_mov_b32 m0, s42
	v_add_u32_e32 v66, 0x2000, v67
	global_load_lds_dwordx4 v[64:65], off
	v_lshl_add_u64 v[64:65], v[218:219], 1, s[2:3]
	v_readfirstlane_b32 s2, v66
	s_mov_b32 m0, s2
	s_nop 0
	global_load_lds_dwordx4 v[64:65], off
.LBB0_137:
	s_xor_b64 s[42:43], s[28:29], -1
	s_mov_b64 s[2:3], -1
	s_andn2_b64 vcc, exec, s[42:43]
	s_cbranch_vccnz .LBB0_139
	ds_read_b128 v[64:67], v163
	ds_read_b128 v[68:71], v163 offset:4096
	s_mov_b64 s[2:3], 0
	s_waitcnt lgkmcnt(2)
	v_mfma_f32_32x32x16_bf16 v[112:127], v[164:167], v[132:135], 0
	v_mfma_f32_32x32x16_bf16 v[96:111], v[168:171], v[132:135], 0
	v_mfma_f32_32x32x16_bf16 v[80:95], v[164:167], v[148:151], 0
	v_mfma_f32_32x32x16_bf16 v[112:127], v[172:175], v[136:139], v[112:127]
	v_mfma_f32_32x32x16_bf16 v[96:111], v[176:179], v[136:139], v[96:111]
	v_mfma_f32_32x32x16_bf16 v[80:95], v[172:175], v[152:155], v[80:95]
	v_mfma_f32_32x32x16_bf16 v[112:127], v[180:183], v[140:143], v[112:127]
	v_mfma_f32_32x32x16_bf16 v[96:111], v[184:187], v[140:143], v[96:111]
	v_mfma_f32_32x32x16_bf16 v[80:95], v[180:183], v[156:159], v[80:95]
	s_waitcnt lgkmcnt(0)
	v_mfma_f32_32x32x16_bf16 v[112:127], v[64:67], v[128:131], v[112:127]
	v_mfma_f32_32x32x16_bf16 v[96:111], v[68:71], v[128:131], v[96:111]
	v_mfma_f32_32x32x16_bf16 v[80:95], v[64:67], v[144:147], v[80:95]
	v_mfma_f32_32x32x16_bf16 v[64:79], v[68:71], v[144:147], 0
	v_mfma_f32_32x32x16_bf16 v[64:79], v[168:171], v[148:151], v[64:79]
	v_mfma_f32_32x32x16_bf16 v[64:79], v[176:179], v[152:155], v[64:79]
	v_mfma_f32_32x32x16_bf16 v[64:79], v[184:187], v[156:159], v[64:79]
